# in-projection: the second k-loop instance (tile column with the f32 dt outputs) also software-pipelined
# speedup vs baseline: 1.0033x; 1.0018x over previous
.LBB0_1173:
	s_waitcnt lgkmcnt(0)
	s_mov_b32 s99, 0x10000
	s_mov_b32 s100, 0x80
	s_mov_b32 s101, 0
	s_add_i32 m0, s3, 0x10000
	s_nop 0
	global_load_lds_dwordx4 v[130:131], off
	v_lshl_add_u64 v[130:131], v[130:131], 0, s[100:101]
	s_add_i32 m0, s3, 0x18000
	s_nop 0
	global_load_lds_dwordx4 v[138:139], off
	v_lshl_add_u64 v[138:139], v[138:139], 0, s[100:101]
	s_add_i32 m0, s7, 0x10000
	s_nop 0
	global_load_lds_dwordx4 v[132:133], off
	v_lshl_add_u64 v[132:133], v[132:133], 0, s[100:101]
	s_add_i32 m0, s7, 0x18000
	s_nop 0
	global_load_lds_dwordx4 v[140:141], off
	v_lshl_add_u64 v[140:141], v[140:141], 0, s[100:101]
	s_add_i32 m0, s8, 0x10000
	s_nop 0
	global_load_lds_dwordx4 v[134:135], off
	v_lshl_add_u64 v[134:135], v[134:135], 0, s[100:101]
	s_add_i32 m0, s8, 0x18000
	s_nop 0
	global_load_lds_dwordx4 v[142:143], off
	v_lshl_add_u64 v[142:143], v[142:143], 0, s[100:101]
	s_add_i32 m0, s9, 0x10000
	s_nop 0
	global_load_lds_dwordx4 v[136:137], off
	v_lshl_add_u64 v[136:137], v[136:137], 0, s[100:101]
	s_add_i32 m0, s9, 0x18000
	s_nop 0
	global_load_lds_dwordx4 v[144:145], off
	v_lshl_add_u64 v[144:145], v[144:145], 0, s[100:101]
	v_add_u32_e32 v162, v149, v147
	v_add_u32_e32 v128, v149, v146
	ds_read_b128 v[150:153], v162 offset:32768
	ds_read_b128 v[154:157], v162 offset:34816
	ds_read_b128 v[158:161], v162 offset:36864
	ds_read_b128 v[162:165], v162 offset:38912
	ds_read_b128 v[166:169], v128 offset:0
	ds_read_b128 v[170:173], v128 offset:2048
	ds_read_b128 v[174:177], v128 offset:4096
	ds_read_b128 v[180:183], v128 offset:6144
	s_mov_b32 s4, 0
.Lg_inpn_loop:
	ds_read_b128 v[186:189], v128 offset:8192
	ds_read_b128 v[190:193], v128 offset:10240
	ds_read_b128 v[194:197], v128 offset:12288
	ds_read_b128 v[198:201], v128 offset:14336
	s_waitcnt lgkmcnt(4)
	v_mfma_f32_16x16x32_bf16 v[124:127], v[166:169], v[150:153], v[124:127]
	v_mfma_f32_16x16x32_bf16 v[120:123], v[166:169], v[154:157], v[120:123]
	v_mfma_f32_16x16x32_bf16 v[116:119], v[166:169], v[158:161], v[116:119]
	v_mfma_f32_16x16x32_bf16 v[112:115], v[166:169], v[162:165], v[112:115]
	v_mfma_f32_16x16x32_bf16 v[108:111], v[170:173], v[150:153], v[108:111]
	v_mfma_f32_16x16x32_bf16 v[104:107], v[170:173], v[154:157], v[104:107]
	v_mfma_f32_16x16x32_bf16 v[100:103], v[170:173], v[158:161], v[100:103]
	v_mfma_f32_16x16x32_bf16 v[96:99], v[170:173], v[162:165], v[96:99]
	v_mfma_f32_16x16x32_bf16 v[88:91], v[174:177], v[150:153], v[88:91]
	v_mfma_f32_16x16x32_bf16 v[84:87], v[174:177], v[154:157], v[84:87]
	v_mfma_f32_16x16x32_bf16 v[80:83], v[174:177], v[158:161], v[80:83]
	v_mfma_f32_16x16x32_bf16 v[76:79], v[174:177], v[162:165], v[76:79]
	v_mfma_f32_16x16x32_bf16 v[72:75], v[180:183], v[150:153], v[72:75]
	v_mfma_f32_16x16x32_bf16 v[68:71], v[180:183], v[154:157], v[68:71]
	v_mfma_f32_16x16x32_bf16 v[64:67], v[180:183], v[158:161], v[64:67]
	v_mfma_f32_16x16x32_bf16 v[60:63], v[180:183], v[162:165], v[60:63]
	v_add_u32_e32 v180, v148, v147
	v_add_u32_e32 v128, v148, v146
	ds_read_b128 v[166:169], v180 offset:32768
	ds_read_b128 v[170:173], v180 offset:34816
	ds_read_b128 v[174:177], v180 offset:36864
	ds_read_b128 v[180:183], v180 offset:38912
	ds_read_b128 v[202:205], v128 offset:0
	ds_read_b128 v[206:209], v128 offset:2048
	ds_read_b128 v[210:213], v128 offset:4096
	ds_read_b128 v[214:217], v128 offset:6144
	s_waitcnt lgkmcnt(8)
	v_mfma_f32_16x16x32_bf16 v[56:59], v[186:189], v[150:153], v[56:59]
	v_mfma_f32_16x16x32_bf16 v[52:55], v[186:189], v[154:157], v[52:55]
	v_mfma_f32_16x16x32_bf16 v[48:51], v[186:189], v[158:161], v[48:51]
	v_mfma_f32_16x16x32_bf16 v[44:47], v[186:189], v[162:165], v[44:47]
	v_mfma_f32_16x16x32_bf16 v[40:43], v[190:193], v[150:153], v[40:43]
	v_mfma_f32_16x16x32_bf16 v[36:39], v[190:193], v[154:157], v[36:39]
	v_mfma_f32_16x16x32_bf16 v[32:35], v[190:193], v[158:161], v[32:35]
	v_mfma_f32_16x16x32_bf16 v[28:31], v[190:193], v[162:165], v[28:31]
	v_mfma_f32_16x16x32_bf16 v[24:27], v[194:197], v[150:153], v[24:27]
	v_mfma_f32_16x16x32_bf16 v[20:23], v[194:197], v[154:157], v[20:23]
	v_mfma_f32_16x16x32_bf16 v[16:19], v[194:197], v[158:161], v[16:19]
	v_mfma_f32_16x16x32_bf16 v[12:15], v[194:197], v[162:165], v[12:15]
	v_mfma_f32_16x16x32_bf16 v[8:11], v[198:201], v[150:153], v[8:11]
	v_mfma_f32_16x16x32_bf16 v[4:7], v[198:201], v[154:157], v[4:7]
	v_mfma_f32_16x16x32_bf16 v[0:3], v[198:201], v[158:161], v[0:3]
	v_mfma_f32_16x16x32_bf16 v[92:95], v[198:201], v[162:165], v[92:95]
	ds_read_b128 v[150:153], v128 offset:8192
	ds_read_b128 v[154:157], v128 offset:10240
	ds_read_b128 v[158:161], v128 offset:12288
	ds_read_b128 v[162:165], v128 offset:14336
	s_waitcnt lgkmcnt(4)
	v_mfma_f32_16x16x32_bf16 v[124:127], v[202:205], v[166:169], v[124:127]
	v_mfma_f32_16x16x32_bf16 v[120:123], v[202:205], v[170:173], v[120:123]
	v_mfma_f32_16x16x32_bf16 v[116:119], v[202:205], v[174:177], v[116:119]
	v_mfma_f32_16x16x32_bf16 v[112:115], v[202:205], v[180:183], v[112:115]
	v_mfma_f32_16x16x32_bf16 v[108:111], v[206:209], v[166:169], v[108:111]
	v_mfma_f32_16x16x32_bf16 v[104:107], v[206:209], v[170:173], v[104:107]
	v_mfma_f32_16x16x32_bf16 v[100:103], v[206:209], v[174:177], v[100:103]
	v_mfma_f32_16x16x32_bf16 v[96:99], v[206:209], v[180:183], v[96:99]
	v_mfma_f32_16x16x32_bf16 v[88:91], v[210:213], v[166:169], v[88:91]
	v_mfma_f32_16x16x32_bf16 v[84:87], v[210:213], v[170:173], v[84:87]
	v_mfma_f32_16x16x32_bf16 v[80:83], v[210:213], v[174:177], v[80:83]
	v_mfma_f32_16x16x32_bf16 v[76:79], v[210:213], v[180:183], v[76:79]
	v_mfma_f32_16x16x32_bf16 v[72:75], v[214:217], v[166:169], v[72:75]
	v_mfma_f32_16x16x32_bf16 v[68:71], v[214:217], v[170:173], v[68:71]
	v_mfma_f32_16x16x32_bf16 v[64:67], v[214:217], v[174:177], v[64:67]
	v_mfma_f32_16x16x32_bf16 v[60:63], v[214:217], v[180:183], v[60:63]
	s_waitcnt lgkmcnt(0)
	v_mfma_f32_16x16x32_bf16 v[56:59], v[150:153], v[166:169], v[56:59]
	s_waitcnt vmcnt(0)
	s_barrier
	v_add3_u32 v198, v149, v147, s99
	v_add3_u32 v128, v149, v146, s99
	v_mfma_f32_16x16x32_bf16 v[52:55], v[150:153], v[170:173], v[52:55]
	ds_read_b128 v[186:189], v198 offset:32768
	ds_read_b128 v[190:193], v198 offset:34816
	v_mfma_f32_16x16x32_bf16 v[48:51], v[150:153], v[174:177], v[48:51]
	ds_read_b128 v[194:197], v198 offset:36864
	ds_read_b128 v[198:201], v198 offset:38912
	v_mfma_f32_16x16x32_bf16 v[44:47], v[150:153], v[180:183], v[44:47]
	ds_read_b128 v[202:205], v128 offset:0
	ds_read_b128 v[206:209], v128 offset:2048
	v_mfma_f32_16x16x32_bf16 v[40:43], v[154:157], v[166:169], v[40:43]
	ds_read_b128 v[210:213], v128 offset:4096
	ds_read_b128 v[214:217], v128 offset:6144
	s_mov_b32 m0, s3
	v_mfma_f32_16x16x32_bf16 v[36:39], v[154:157], v[170:173], v[36:39]
	global_load_lds_dwordx4 v[130:131], off
	v_lshl_add_u64 v[130:131], v[130:131], 0, s[100:101]
	s_add_i32 m0, s3, 0x8000
	v_mfma_f32_16x16x32_bf16 v[32:35], v[154:157], v[174:177], v[32:35]
	global_load_lds_dwordx4 v[138:139], off
	v_lshl_add_u64 v[138:139], v[138:139], 0, s[100:101]
	s_mov_b32 m0, s7
	v_mfma_f32_16x16x32_bf16 v[28:31], v[154:157], v[180:183], v[28:31]
	global_load_lds_dwordx4 v[132:133], off
	v_lshl_add_u64 v[132:133], v[132:133], 0, s[100:101]
	s_add_i32 m0, s7, 0x8000
	v_mfma_f32_16x16x32_bf16 v[24:27], v[158:161], v[166:169], v[24:27]
	global_load_lds_dwordx4 v[140:141], off
	v_lshl_add_u64 v[140:141], v[140:141], 0, s[100:101]
	s_mov_b32 m0, s8
	v_mfma_f32_16x16x32_bf16 v[20:23], v[158:161], v[170:173], v[20:23]
	global_load_lds_dwordx4 v[134:135], off
	v_lshl_add_u64 v[134:135], v[134:135], 0, s[100:101]
	s_add_i32 m0, s8, 0x8000
	v_mfma_f32_16x16x32_bf16 v[16:19], v[158:161], v[174:177], v[16:19]
	global_load_lds_dwordx4 v[142:143], off
	v_lshl_add_u64 v[142:143], v[142:143], 0, s[100:101]
	s_mov_b32 m0, s9
	v_mfma_f32_16x16x32_bf16 v[12:15], v[158:161], v[180:183], v[12:15]
	global_load_lds_dwordx4 v[136:137], off
	v_lshl_add_u64 v[136:137], v[136:137], 0, s[100:101]
	s_add_i32 m0, s9, 0x8000
	v_mfma_f32_16x16x32_bf16 v[8:11], v[162:165], v[166:169], v[8:11]
	global_load_lds_dwordx4 v[144:145], off
	v_lshl_add_u64 v[144:145], v[144:145], 0, s[100:101]
	v_mfma_f32_16x16x32_bf16 v[4:7], v[162:165], v[170:173], v[4:7]
	v_mfma_f32_16x16x32_bf16 v[0:3], v[162:165], v[174:177], v[0:3]
	v_mfma_f32_16x16x32_bf16 v[92:95], v[162:165], v[180:183], v[92:95]
	ds_read_b128 v[150:153], v128 offset:8192
	ds_read_b128 v[154:157], v128 offset:10240
	ds_read_b128 v[158:161], v128 offset:12288
	ds_read_b128 v[162:165], v128 offset:14336
	s_waitcnt lgkmcnt(4)
	v_mfma_f32_16x16x32_bf16 v[124:127], v[202:205], v[186:189], v[124:127]
	v_mfma_f32_16x16x32_bf16 v[120:123], v[202:205], v[190:193], v[120:123]
	v_mfma_f32_16x16x32_bf16 v[116:119], v[202:205], v[194:197], v[116:119]
	v_mfma_f32_16x16x32_bf16 v[112:115], v[202:205], v[198:201], v[112:115]
	v_mfma_f32_16x16x32_bf16 v[108:111], v[206:209], v[186:189], v[108:111]
	v_mfma_f32_16x16x32_bf16 v[104:107], v[206:209], v[190:193], v[104:107]
	v_mfma_f32_16x16x32_bf16 v[100:103], v[206:209], v[194:197], v[100:103]
	v_mfma_f32_16x16x32_bf16 v[96:99], v[206:209], v[198:201], v[96:99]
	v_mfma_f32_16x16x32_bf16 v[88:91], v[210:213], v[186:189], v[88:91]
	v_mfma_f32_16x16x32_bf16 v[84:87], v[210:213], v[190:193], v[84:87]
	v_mfma_f32_16x16x32_bf16 v[80:83], v[210:213], v[194:197], v[80:83]
	v_mfma_f32_16x16x32_bf16 v[76:79], v[210:213], v[198:201], v[76:79]
	v_mfma_f32_16x16x32_bf16 v[72:75], v[214:217], v[186:189], v[72:75]
	v_mfma_f32_16x16x32_bf16 v[68:71], v[214:217], v[190:193], v[68:71]
	v_mfma_f32_16x16x32_bf16 v[64:67], v[214:217], v[194:197], v[64:67]
	v_mfma_f32_16x16x32_bf16 v[60:63], v[214:217], v[198:201], v[60:63]
	v_add3_u32 v214, v148, v147, s99
	v_add3_u32 v128, v148, v146, s99
	ds_read_b128 v[202:205], v214 offset:32768
	ds_read_b128 v[206:209], v214 offset:34816
	ds_read_b128 v[210:213], v214 offset:36864
	ds_read_b128 v[214:217], v214 offset:38912
	ds_read_b128 v[166:169], v128 offset:0
	ds_read_b128 v[170:173], v128 offset:2048
	ds_read_b128 v[174:177], v128 offset:4096
	ds_read_b128 v[180:183], v128 offset:6144
	s_waitcnt lgkmcnt(8)
	v_mfma_f32_16x16x32_bf16 v[56:59], v[150:153], v[186:189], v[56:59]
	v_mfma_f32_16x16x32_bf16 v[52:55], v[150:153], v[190:193], v[52:55]
	v_mfma_f32_16x16x32_bf16 v[48:51], v[150:153], v[194:197], v[48:51]
	v_mfma_f32_16x16x32_bf16 v[44:47], v[150:153], v[198:201], v[44:47]
	v_mfma_f32_16x16x32_bf16 v[40:43], v[154:157], v[186:189], v[40:43]
	v_mfma_f32_16x16x32_bf16 v[36:39], v[154:157], v[190:193], v[36:39]
	v_mfma_f32_16x16x32_bf16 v[32:35], v[154:157], v[194:197], v[32:35]
	v_mfma_f32_16x16x32_bf16 v[28:31], v[154:157], v[198:201], v[28:31]
	v_mfma_f32_16x16x32_bf16 v[24:27], v[158:161], v[186:189], v[24:27]
	v_mfma_f32_16x16x32_bf16 v[20:23], v[158:161], v[190:193], v[20:23]
	v_mfma_f32_16x16x32_bf16 v[16:19], v[158:161], v[194:197], v[16:19]
	v_mfma_f32_16x16x32_bf16 v[12:15], v[158:161], v[198:201], v[12:15]
	v_mfma_f32_16x16x32_bf16 v[8:11], v[162:165], v[186:189], v[8:11]
	v_mfma_f32_16x16x32_bf16 v[4:7], v[162:165], v[190:193], v[4:7]
	v_mfma_f32_16x16x32_bf16 v[0:3], v[162:165], v[194:197], v[0:3]
	v_mfma_f32_16x16x32_bf16 v[92:95], v[162:165], v[198:201], v[92:95]
	ds_read_b128 v[186:189], v128 offset:8192
	ds_read_b128 v[190:193], v128 offset:10240
	ds_read_b128 v[194:197], v128 offset:12288
	ds_read_b128 v[198:201], v128 offset:14336
	s_waitcnt lgkmcnt(4)
	v_mfma_f32_16x16x32_bf16 v[124:127], v[166:169], v[202:205], v[124:127]
	v_mfma_f32_16x16x32_bf16 v[120:123], v[166:169], v[206:209], v[120:123]
	v_mfma_f32_16x16x32_bf16 v[116:119], v[166:169], v[210:213], v[116:119]
	v_mfma_f32_16x16x32_bf16 v[112:115], v[166:169], v[214:217], v[112:115]
	v_mfma_f32_16x16x32_bf16 v[108:111], v[170:173], v[202:205], v[108:111]
	v_mfma_f32_16x16x32_bf16 v[104:107], v[170:173], v[206:209], v[104:107]
	v_mfma_f32_16x16x32_bf16 v[100:103], v[170:173], v[210:213], v[100:103]
	v_mfma_f32_16x16x32_bf16 v[96:99], v[170:173], v[214:217], v[96:99]
	v_mfma_f32_16x16x32_bf16 v[88:91], v[174:177], v[202:205], v[88:91]
	v_mfma_f32_16x16x32_bf16 v[84:87], v[174:177], v[206:209], v[84:87]
	v_mfma_f32_16x16x32_bf16 v[80:83], v[174:177], v[210:213], v[80:83]
	v_mfma_f32_16x16x32_bf16 v[76:79], v[174:177], v[214:217], v[76:79]
	v_mfma_f32_16x16x32_bf16 v[72:75], v[180:183], v[202:205], v[72:75]
	v_mfma_f32_16x16x32_bf16 v[68:71], v[180:183], v[206:209], v[68:71]
	v_mfma_f32_16x16x32_bf16 v[64:67], v[180:183], v[210:213], v[64:67]
	v_mfma_f32_16x16x32_bf16 v[60:63], v[180:183], v[214:217], v[60:63]
	s_waitcnt lgkmcnt(0)
	v_mfma_f32_16x16x32_bf16 v[56:59], v[186:189], v[202:205], v[56:59]
	s_waitcnt vmcnt(0)
	s_barrier
	v_add_u32_e32 v162, v149, v147
	v_add_u32_e32 v128, v149, v146
	v_mfma_f32_16x16x32_bf16 v[52:55], v[186:189], v[206:209], v[52:55]
	ds_read_b128 v[150:153], v162 offset:32768
	ds_read_b128 v[154:157], v162 offset:34816
	v_mfma_f32_16x16x32_bf16 v[48:51], v[186:189], v[210:213], v[48:51]
	ds_read_b128 v[158:161], v162 offset:36864
	ds_read_b128 v[162:165], v162 offset:38912
	v_mfma_f32_16x16x32_bf16 v[44:47], v[186:189], v[214:217], v[44:47]
	ds_read_b128 v[166:169], v128 offset:0
	ds_read_b128 v[170:173], v128 offset:2048
	v_mfma_f32_16x16x32_bf16 v[40:43], v[190:193], v[202:205], v[40:43]
	ds_read_b128 v[174:177], v128 offset:4096
	ds_read_b128 v[180:183], v128 offset:6144
	s_add_i32 m0, s3, 0x10000
	v_mfma_f32_16x16x32_bf16 v[36:39], v[190:193], v[206:209], v[36:39]
	global_load_lds_dwordx4 v[130:131], off
	v_lshl_add_u64 v[130:131], v[130:131], 0, s[100:101]
	s_add_i32 m0, s3, 0x18000
	v_mfma_f32_16x16x32_bf16 v[32:35], v[190:193], v[210:213], v[32:35]
	global_load_lds_dwordx4 v[138:139], off
	v_lshl_add_u64 v[138:139], v[138:139], 0, s[100:101]
	s_add_i32 m0, s7, 0x10000
	v_mfma_f32_16x16x32_bf16 v[28:31], v[190:193], v[214:217], v[28:31]
	global_load_lds_dwordx4 v[132:133], off
	v_lshl_add_u64 v[132:133], v[132:133], 0, s[100:101]
	s_add_i32 m0, s7, 0x18000
	v_mfma_f32_16x16x32_bf16 v[24:27], v[194:197], v[202:205], v[24:27]
	global_load_lds_dwordx4 v[140:141], off
	v_lshl_add_u64 v[140:141], v[140:141], 0, s[100:101]
	s_add_i32 m0, s8, 0x10000
	v_mfma_f32_16x16x32_bf16 v[20:23], v[194:197], v[206:209], v[20:23]
	global_load_lds_dwordx4 v[134:135], off
	v_lshl_add_u64 v[134:135], v[134:135], 0, s[100:101]
	s_add_i32 m0, s8, 0x18000
	v_mfma_f32_16x16x32_bf16 v[16:19], v[194:197], v[210:213], v[16:19]
	global_load_lds_dwordx4 v[142:143], off
	v_lshl_add_u64 v[142:143], v[142:143], 0, s[100:101]
	s_add_i32 m0, s9, 0x10000
	v_mfma_f32_16x16x32_bf16 v[12:15], v[194:197], v[214:217], v[12:15]
	global_load_lds_dwordx4 v[136:137], off
	v_lshl_add_u64 v[136:137], v[136:137], 0, s[100:101]
	s_add_i32 m0, s9, 0x18000
	v_mfma_f32_16x16x32_bf16 v[8:11], v[198:201], v[202:205], v[8:11]
	global_load_lds_dwordx4 v[144:145], off
	v_lshl_add_u64 v[144:145], v[144:145], 0, s[100:101]
	v_mfma_f32_16x16x32_bf16 v[4:7], v[198:201], v[206:209], v[4:7]
	v_mfma_f32_16x16x32_bf16 v[0:3], v[198:201], v[210:213], v[0:3]
	v_mfma_f32_16x16x32_bf16 v[92:95], v[198:201], v[214:217], v[92:95]
	s_add_u32 s4, s4, 0x100
	s_cmpk_lg_i32 s4, 0x700
	s_cbranch_scc1 .Lg_inpn_loop
	ds_read_b128 v[186:189], v128 offset:8192
	ds_read_b128 v[190:193], v128 offset:10240
	ds_read_b128 v[194:197], v128 offset:12288
	ds_read_b128 v[198:201], v128 offset:14336
	s_waitcnt lgkmcnt(4)
	v_mfma_f32_16x16x32_bf16 v[124:127], v[166:169], v[150:153], v[124:127]
	v_mfma_f32_16x16x32_bf16 v[120:123], v[166:169], v[154:157], v[120:123]
	v_mfma_f32_16x16x32_bf16 v[116:119], v[166:169], v[158:161], v[116:119]
	v_mfma_f32_16x16x32_bf16 v[112:115], v[166:169], v[162:165], v[112:115]
	v_mfma_f32_16x16x32_bf16 v[108:111], v[170:173], v[150:153], v[108:111]
	v_mfma_f32_16x16x32_bf16 v[104:107], v[170:173], v[154:157], v[104:107]
	v_mfma_f32_16x16x32_bf16 v[100:103], v[170:173], v[158:161], v[100:103]
	v_mfma_f32_16x16x32_bf16 v[96:99], v[170:173], v[162:165], v[96:99]
	v_mfma_f32_16x16x32_bf16 v[88:91], v[174:177], v[150:153], v[88:91]
	v_mfma_f32_16x16x32_bf16 v[84:87], v[174:177], v[154:157], v[84:87]
	v_mfma_f32_16x16x32_bf16 v[80:83], v[174:177], v[158:161], v[80:83]
	v_mfma_f32_16x16x32_bf16 v[76:79], v[174:177], v[162:165], v[76:79]
	v_mfma_f32_16x16x32_bf16 v[72:75], v[180:183], v[150:153], v[72:75]
	v_mfma_f32_16x16x32_bf16 v[68:71], v[180:183], v[154:157], v[68:71]
	v_mfma_f32_16x16x32_bf16 v[64:67], v[180:183], v[158:161], v[64:67]
	v_mfma_f32_16x16x32_bf16 v[60:63], v[180:183], v[162:165], v[60:63]
	v_add_u32_e32 v180, v148, v147
	v_add_u32_e32 v128, v148, v146
	ds_read_b128 v[166:169], v180 offset:32768
	ds_read_b128 v[170:173], v180 offset:34816
	ds_read_b128 v[174:177], v180 offset:36864
	ds_read_b128 v[180:183], v180 offset:38912
	ds_read_b128 v[202:205], v128 offset:0
	ds_read_b128 v[206:209], v128 offset:2048
	ds_read_b128 v[210:213], v128 offset:4096
	ds_read_b128 v[214:217], v128 offset:6144
	s_waitcnt lgkmcnt(8)
	v_mfma_f32_16x16x32_bf16 v[56:59], v[186:189], v[150:153], v[56:59]
	v_mfma_f32_16x16x32_bf16 v[52:55], v[186:189], v[154:157], v[52:55]
	v_mfma_f32_16x16x32_bf16 v[48:51], v[186:189], v[158:161], v[48:51]
	v_mfma_f32_16x16x32_bf16 v[44:47], v[186:189], v[162:165], v[44:47]
	v_mfma_f32_16x16x32_bf16 v[40:43], v[190:193], v[150:153], v[40:43]
	v_mfma_f32_16x16x32_bf16 v[36:39], v[190:193], v[154:157], v[36:39]
	v_mfma_f32_16x16x32_bf16 v[32:35], v[190:193], v[158:161], v[32:35]
	v_mfma_f32_16x16x32_bf16 v[28:31], v[190:193], v[162:165], v[28:31]
	v_mfma_f32_16x16x32_bf16 v[24:27], v[194:197], v[150:153], v[24:27]
	v_mfma_f32_16x16x32_bf16 v[20:23], v[194:197], v[154:157], v[20:23]
	v_mfma_f32_16x16x32_bf16 v[16:19], v[194:197], v[158:161], v[16:19]
	v_mfma_f32_16x16x32_bf16 v[12:15], v[194:197], v[162:165], v[12:15]
	v_mfma_f32_16x16x32_bf16 v[8:11], v[198:201], v[150:153], v[8:11]
	v_mfma_f32_16x16x32_bf16 v[4:7], v[198:201], v[154:157], v[4:7]
	v_mfma_f32_16x16x32_bf16 v[0:3], v[198:201], v[158:161], v[0:3]
	v_mfma_f32_16x16x32_bf16 v[92:95], v[198:201], v[162:165], v[92:95]
	ds_read_b128 v[150:153], v128 offset:8192
	ds_read_b128 v[154:157], v128 offset:10240
	ds_read_b128 v[158:161], v128 offset:12288
	ds_read_b128 v[162:165], v128 offset:14336
	s_waitcnt lgkmcnt(4)
	v_mfma_f32_16x16x32_bf16 v[124:127], v[202:205], v[166:169], v[124:127]
	v_mfma_f32_16x16x32_bf16 v[120:123], v[202:205], v[170:173], v[120:123]
	v_mfma_f32_16x16x32_bf16 v[116:119], v[202:205], v[174:177], v[116:119]
	v_mfma_f32_16x16x32_bf16 v[112:115], v[202:205], v[180:183], v[112:115]
	v_mfma_f32_16x16x32_bf16 v[108:111], v[206:209], v[166:169], v[108:111]
	v_mfma_f32_16x16x32_bf16 v[104:107], v[206:209], v[170:173], v[104:107]
	v_mfma_f32_16x16x32_bf16 v[100:103], v[206:209], v[174:177], v[100:103]
	v_mfma_f32_16x16x32_bf16 v[96:99], v[206:209], v[180:183], v[96:99]
	v_mfma_f32_16x16x32_bf16 v[88:91], v[210:213], v[166:169], v[88:91]
	v_mfma_f32_16x16x32_bf16 v[84:87], v[210:213], v[170:173], v[84:87]
	v_mfma_f32_16x16x32_bf16 v[80:83], v[210:213], v[174:177], v[80:83]
	v_mfma_f32_16x16x32_bf16 v[76:79], v[210:213], v[180:183], v[76:79]
	v_mfma_f32_16x16x32_bf16 v[72:75], v[214:217], v[166:169], v[72:75]
	v_mfma_f32_16x16x32_bf16 v[68:71], v[214:217], v[170:173], v[68:71]
	v_mfma_f32_16x16x32_bf16 v[64:67], v[214:217], v[174:177], v[64:67]
	v_mfma_f32_16x16x32_bf16 v[60:63], v[214:217], v[180:183], v[60:63]
	s_waitcnt lgkmcnt(0)
	v_mfma_f32_16x16x32_bf16 v[56:59], v[150:153], v[166:169], v[56:59]
	s_waitcnt vmcnt(0)
	s_barrier
	v_mfma_f32_16x16x32_bf16 v[52:55], v[150:153], v[170:173], v[52:55]
	v_mfma_f32_16x16x32_bf16 v[48:51], v[150:153], v[174:177], v[48:51]
	v_mfma_f32_16x16x32_bf16 v[44:47], v[150:153], v[180:183], v[44:47]
	v_mfma_f32_16x16x32_bf16 v[40:43], v[154:157], v[166:169], v[40:43]
	v_mfma_f32_16x16x32_bf16 v[36:39], v[154:157], v[170:173], v[36:39]
	v_mfma_f32_16x16x32_bf16 v[32:35], v[154:157], v[174:177], v[32:35]
	v_mfma_f32_16x16x32_bf16 v[28:31], v[154:157], v[180:183], v[28:31]
	v_mfma_f32_16x16x32_bf16 v[24:27], v[158:161], v[166:169], v[24:27]
	v_mfma_f32_16x16x32_bf16 v[20:23], v[158:161], v[170:173], v[20:23]
	v_mfma_f32_16x16x32_bf16 v[16:19], v[158:161], v[174:177], v[16:19]
	v_mfma_f32_16x16x32_bf16 v[12:15], v[158:161], v[180:183], v[12:15]
	v_mfma_f32_16x16x32_bf16 v[8:11], v[162:165], v[166:169], v[8:11]
	v_mfma_f32_16x16x32_bf16 v[4:7], v[162:165], v[170:173], v[4:7]
	v_mfma_f32_16x16x32_bf16 v[0:3], v[162:165], v[174:177], v[0:3]
	v_mfma_f32_16x16x32_bf16 v[92:95], v[162:165], v[180:183], v[92:95]
	s_mov_b32 s11, 0x10000
	v_add_u32_e32 v128, s11, v149
	v_add_u32_e32 v142, v128, v147
	v_add_u32_e32 v128, v128, v146
	ds_read_b128 v[130:133], v142 offset:32768
	ds_read_b128 v[134:137], v142 offset:34816
	ds_read_b128 v[138:141], v142 offset:36864
	ds_read_b128 v[142:145], v142 offset:38912
	ds_read_b128 v[150:153], v128
	ds_read_b128 v[154:157], v128 offset:2048
	ds_read_b128 v[158:161], v128 offset:4096
	ds_read_b128 v[162:165], v128 offset:6144
	ds_read_b128 v[166:169], v128 offset:8192
	ds_read_b128 v[170:173], v128 offset:10240
	ds_read_b128 v[174:177], v128 offset:12288
	ds_read_b128 v[180:183], v128 offset:14336
	s_lshl_b32 s4, s2, 8
	s_waitcnt lgkmcnt(0)
	v_mfma_f32_16x16x32_bf16 v[124:127], v[150:153], v[130:133], v[124:127]
	v_mfma_f32_16x16x32_bf16 v[120:123], v[150:153], v[134:137], v[120:123]
	v_mfma_f32_16x16x32_bf16 v[116:119], v[150:153], v[138:141], v[116:119]
	v_mfma_f32_16x16x32_bf16 v[112:115], v[150:153], v[142:145], v[112:115]
	v_mfma_f32_16x16x32_bf16 v[108:111], v[154:157], v[130:133], v[108:111]
	v_mfma_f32_16x16x32_bf16 v[104:107], v[154:157], v[134:137], v[104:107]
	v_mfma_f32_16x16x32_bf16 v[100:103], v[154:157], v[138:141], v[100:103]
	v_mfma_f32_16x16x32_bf16 v[96:99], v[154:157], v[142:145], v[96:99]
	v_mfma_f32_16x16x32_bf16 v[150:153], v[158:161], v[130:133], v[88:91]
	v_mfma_f32_16x16x32_bf16 v[84:87], v[158:161], v[134:137], v[84:87]
	v_mfma_f32_16x16x32_bf16 v[154:157], v[158:161], v[138:141], v[80:83]
	v_mfma_f32_16x16x32_bf16 v[76:79], v[158:161], v[142:145], v[76:79]
	v_mfma_f32_16x16x32_bf16 v[72:75], v[162:165], v[130:133], v[72:75]
	v_mfma_f32_16x16x32_bf16 v[68:71], v[162:165], v[134:137], v[68:71]
	v_mfma_f32_16x16x32_bf16 v[64:67], v[162:165], v[138:141], v[64:67]
	v_mfma_f32_16x16x32_bf16 v[158:161], v[162:165], v[142:145], v[60:63]
	s_nop 2
	v_add_u32_e32 v60, s11, v148
	v_add_u32_e32 v61, v60, v147
	v_add_u32_e32 v88, v60, v146
	ds_read_b128 v[162:165], v61 offset:32768
	ds_read_b128 v[186:189], v61 offset:34816
	ds_read_b128 v[190:193], v61 offset:36864
	ds_read_b128 v[194:197], v61 offset:38912
	ds_read_b128 v[60:63], v88
	ds_read_b128 v[80:83], v88 offset:2048
	ds_read_b128 v[146:149], v88 offset:4096
	ds_read_b128 v[198:201], v88 offset:6144
	v_mfma_f32_16x16x32_bf16 v[202:205], v[166:169], v[130:133], v[56:59]
	v_mfma_f32_16x16x32_bf16 v[206:209], v[166:169], v[134:137], v[52:55]
	v_mfma_f32_16x16x32_bf16 v[210:213], v[166:169], v[138:141], v[48:51]
	v_mfma_f32_16x16x32_bf16 v[44:47], v[166:169], v[142:145], v[44:47]
	v_mfma_f32_16x16x32_bf16 v[166:169], v[170:173], v[130:133], v[40:43]
	v_mfma_f32_16x16x32_bf16 v[36:39], v[170:173], v[134:137], v[36:39]
	v_mfma_f32_16x16x32_bf16 v[32:35], v[170:173], v[138:141], v[32:35]
	v_mfma_f32_16x16x32_bf16 v[214:217], v[174:177], v[130:133], v[24:27]
	v_mfma_f32_16x16x32_bf16 v[130:133], v[180:183], v[130:133], v[8:11]
	v_mfma_f32_16x16x32_bf16 v[4:7], v[180:183], v[134:137], v[4:7]
	v_mfma_f32_16x16x32_bf16 v[170:173], v[170:173], v[142:145], v[28:31]
	v_mfma_f32_16x16x32_bf16 v[218:221], v[174:177], v[134:137], v[20:23]
	v_mfma_f32_16x16x32_bf16 v[222:225], v[174:177], v[138:141], v[16:19]
	v_mfma_f32_16x16x32_bf16 v[174:177], v[174:177], v[142:145], v[12:15]
	v_mfma_f32_16x16x32_bf16 v[134:137], v[180:183], v[138:141], v[0:3]
	v_mfma_f32_16x16x32_bf16 v[138:141], v[180:183], v[142:145], v[92:95]
	s_nop 1
	ds_read_b128 v[0:3], v88 offset:8192
	ds_read_b128 v[12:15], v88 offset:10240
	ds_read_b128 v[142:145], v88 offset:12288
	ds_read_b128 v[180:183], v88 offset:14336
	s_waitcnt lgkmcnt(0)
	v_mfma_f32_16x16x32_bf16 v[124:127], v[60:63], v[162:165], v[124:127]
	v_mfma_f32_16x16x32_bf16 v[88:91], v[60:63], v[186:189], v[120:123]
	v_mfma_f32_16x16x32_bf16 v[56:59], v[60:63], v[190:193], v[116:119]
	v_mfma_f32_16x16x32_bf16 v[24:27], v[60:63], v[194:197], v[112:115]
	v_mfma_f32_16x16x32_bf16 v[120:123], v[80:83], v[162:165], v[108:111]
	v_mfma_f32_16x16x32_bf16 v[92:95], v[80:83], v[186:189], v[104:107]
	v_mfma_f32_16x16x32_bf16 v[60:63], v[80:83], v[190:193], v[100:103]
	v_mfma_f32_16x16x32_bf16 v[28:31], v[80:83], v[194:197], v[96:99]
	v_mfma_f32_16x16x32_bf16 v[112:115], v[146:149], v[162:165], v[150:153]
	v_mfma_f32_16x16x32_bf16 v[80:83], v[146:149], v[186:189], v[84:87]
	v_mfma_f32_16x16x32_bf16 v[48:51], v[146:149], v[190:193], v[154:157]
	v_mfma_f32_16x16x32_bf16 v[16:19], v[146:149], v[194:197], v[76:79]
	v_mfma_f32_16x16x32_bf16 v[116:119], v[198:201], v[162:165], v[72:75]
	v_mfma_f32_16x16x32_bf16 v[84:87], v[198:201], v[186:189], v[68:71]
	v_mfma_f32_16x16x32_bf16 v[52:55], v[198:201], v[190:193], v[64:67]
	v_mfma_f32_16x16x32_bf16 v[20:23], v[198:201], v[194:197], v[158:161]
	s_waitcnt vmcnt(0)
	v_mov_b32_e32 v154, v184
	s_waitcnt lgkmcnt(0)
	s_barrier
	v_mfma_f32_16x16x32_bf16 v[68:71], v[180:183], v[186:189], v[4:7]
	v_bfe_u32 v128, v154, 6, 2
	v_and_b32_e32 v152, 15, v154
	v_ashrrev_i32_e32 v153, 8, v154
	v_lshrrev_b32_e32 v4, 2, v154
	v_and_b32_e32 v155, 12, v4
	v_lshlrev_b32_e32 v4, 6, v128
	v_mfma_f32_16x16x32_bf16 v[104:107], v[0:3], v[162:165], v[202:205]
	s_cmp_lt_i32 s6, 12
	s_mov_b64 s[2:3], -1
	v_mfma_f32_16x16x32_bf16 v[72:75], v[0:3], v[186:189], v[206:209]
	v_mfma_f32_16x16x32_bf16 v[40:43], v[0:3], v[190:193], v[210:213]
	v_mfma_f32_16x16x32_bf16 v[8:11], v[0:3], v[194:197], v[44:47]
	v_mfma_f32_16x16x32_bf16 v[108:111], v[12:15], v[162:165], v[166:169]
	v_mfma_f32_16x16x32_bf16 v[76:79], v[12:15], v[186:189], v[36:39]
	v_mfma_f32_16x16x32_bf16 v[44:47], v[12:15], v[190:193], v[32:35]
	v_mfma_f32_16x16x32_bf16 v[12:15], v[12:15], v[194:197], v[170:173]
	v_mfma_f32_16x16x32_bf16 v[96:99], v[142:145], v[162:165], v[214:217]
	v_mfma_f32_16x16x32_bf16 v[64:67], v[142:145], v[186:189], v[218:221]
	v_mfma_f32_16x16x32_bf16 v[32:35], v[142:145], v[190:193], v[222:225]
	v_mfma_f32_16x16x32_bf16 v[0:3], v[142:145], v[194:197], v[174:177]
	v_mfma_f32_16x16x32_bf16 v[100:103], v[180:183], v[162:165], v[130:133]
	v_mfma_f32_16x16x32_bf16 v[36:39], v[180:183], v[190:193], v[134:137]
	s_nop 1
	v_or3_b32 v130, v4, v152, s4
	v_cvt_pk_bf16_f32 v132, v124, v125
	v_cvt_pk_bf16_f32 v133, v126, v127
	v_mfma_f32_16x16x32_bf16 v[4:7], v[180:183], v[194:197], v[138:141]
	s_cbranch_scc0 .LBB0_1176
	s_and_b64 vcc, exec, s[2:3]
	s_cbranch_vccz .LBB0_1171
	s_branch .LBB0_1657
